# v094 + wave 0 touches the next DSA item's 8 query rows (1 KB each) while the last logits batch runs, so the next item's prologue loads hit in L2
# speedup vs baseline: 1.0017x; 1.0017x over previous
; #define LAS __attribute__((address_space(3)))
;     ...
;           for (int jj = 0; jj < 4; ++jj) {
;               const int rho = jj * 16 + c16, slot = b * 64 + rho;
;               f32x4 a = {0.f, 0.f, 0.f, 0.f}; float ss = 0.f;
; #pragma unroll
;               for (int ks = 0; ks < 4; ++ks) {
; #pragma unroll
;                   for (int e = 0; e < 4; ++e) asm("v_dot2_f32_bf16 %0, %1, %1, %0" : "+v"(ss) : "v"(w[jj][ks][e]));
;                   a = __builtin_amdgcn_mfma_f32_16x16x32_bf16(qa[ks], *reinterpret_cast<const bf16x8*>(&w[jj][ks]), a, 0, 0, 0);
;                   *(LAS u32x4*)(wbase + rho * 256 + (((ks * 4 + quad) ^ fsw) << 4)) = w[jj][ks]; }
;               ss += __shfl_xor(ss, 16); ss += __shfl_xor(ss, 32);
;               const float rstd = rsqrtf(ss * (1.f / 128.f) + EPS);
;               const float av = quad == 0 ? a[0] : (quad == 1 ? a[1] : (quad == 2 ? a[2] : a[3]));
;               rsv[jj] = rstd; lgv[jj] = (slot < kcount) ? av * rstd * 0.08838834764831845f : -__builtin_inff();
;           }
.LBB0_928:
	s_add_i32 s0, s24, 1
	s_cmp_ge_i32 s0, s23
	s_cbranch_scc0 .Ldsa_steady
	s_waitcnt vmcnt(12)
	ds_write_b128 v244, v[26:29]
	ds_write_b128 v245, v[18:21]
	ds_write_b128 v246, v[22:25]
	ds_write_b128 v247, v[30:33]
	v_add_u32_e32 v0, v146, v147
	ds_read_b128 v[232:235], v0
	v_add_u32_e32 v0, v146, v148
	ds_read_b128 v[236:239], v0
	v_add_u32_e32 v0, v146, v149
	ds_read_b128 v[240:243], v0
	v_add_u32_e32 v0, v146, v150
	v_mov_b32_e32 v118, 0
	s_waitcnt lgkmcnt(2)
	v_dot2_f32_bf16 v118, v232, v232, v118
	v_dot2_f32_bf16 v118, v233, v233, v118
	v_dot2_f32_bf16 v118, v234, v234, v118
	v_dot2_f32_bf16 v118, v235, v235, v118
	v_mfma_f32_16x16x32_bf16 v[114:117], v[2:5], v[232:235], 0
	ds_read_b128 v[232:235], v0
	s_waitcnt lgkmcnt(2)
	v_dot2_f32_bf16 v118, v236, v236, v118
	v_dot2_f32_bf16 v118, v237, v237, v118
	v_dot2_f32_bf16 v118, v238, v238, v118
	v_dot2_f32_bf16 v118, v239, v239, v118
	v_mfma_f32_16x16x32_bf16 v[114:117], v[6:9], v[236:239], v[114:117]
	s_waitcnt lgkmcnt(1)
	v_dot2_f32_bf16 v118, v240, v240, v118
	v_dot2_f32_bf16 v118, v241, v241, v118
	v_dot2_f32_bf16 v118, v242, v242, v118
	v_dot2_f32_bf16 v118, v243, v243, v118
	v_mfma_f32_16x16x32_bf16 v[114:117], v[10:13], v[240:243], v[114:117]
	s_waitcnt lgkmcnt(0)
	v_dot2_f32_bf16 v118, v232, v232, v118
	v_dot2_f32_bf16 v118, v233, v233, v118
	v_dot2_f32_bf16 v118, v234, v234, v118
	v_dot2_f32_bf16 v118, v235, v235, v118
	v_mfma_f32_16x16x32_bf16 v[114:117], v[14:17], v[232:235], v[114:117]
	s_nop 2
	v_mov_b32_e32 v119, v118
	s_nop 1
	v_permlane16_swap_b32_e32 v118, v119
	v_add_f32_e32 v161, v118, v119
	ds_bpermute_b32 v172, v248, v161
	v_cndmask_b32_e64 v114, v114, v115, s[66:67]
	v_cndmask_b32_e64 v114, v114, v116, s[40:41]
	v_cndmask_b32_e64 v114, v114, v117, s[68:69]
	s_waitcnt vmcnt(8)
	ds_write_b128 v244, v[42:45] offset:4096
	ds_write_b128 v245, v[34:37] offset:4096
	ds_write_b128 v246, v[38:41] offset:4096
	ds_write_b128 v247, v[46:49] offset:4096
	v_add_u32_e32 v0, v146, v147
	ds_read_b128 v[232:235], v0 offset:4096
	v_add_u32_e32 v0, v146, v148
	ds_read_b128 v[236:239], v0 offset:4096
	v_add_u32_e32 v0, v146, v149
	ds_read_b128 v[240:243], v0 offset:4096
	v_add_u32_e32 v0, v146, v150
	v_mov_b32_e32 v115, 0
	s_waitcnt lgkmcnt(2)
	v_dot2_f32_bf16 v115, v232, v232, v115
	v_dot2_f32_bf16 v115, v233, v233, v115
	v_dot2_f32_bf16 v115, v234, v234, v115
	v_dot2_f32_bf16 v115, v235, v235, v115
	v_mfma_f32_16x16x32_bf16 v[116:119], v[2:5], v[232:235], 0
	ds_read_b128 v[232:235], v0 offset:4096
	s_waitcnt lgkmcnt(2)
	v_dot2_f32_bf16 v115, v236, v236, v115
	v_dot2_f32_bf16 v115, v237, v237, v115
	v_dot2_f32_bf16 v115, v238, v238, v115
	v_dot2_f32_bf16 v115, v239, v239, v115
	v_mfma_f32_16x16x32_bf16 v[116:119], v[6:9], v[236:239], v[116:119]
	s_waitcnt lgkmcnt(1)
	v_dot2_f32_bf16 v115, v240, v240, v115
	v_dot2_f32_bf16 v115, v241, v241, v115
	v_dot2_f32_bf16 v115, v242, v242, v115
	v_dot2_f32_bf16 v115, v243, v243, v115
	v_mfma_f32_16x16x32_bf16 v[116:119], v[10:13], v[240:243], v[116:119]
	s_waitcnt lgkmcnt(0)
	v_dot2_f32_bf16 v115, v232, v232, v115
	v_dot2_f32_bf16 v115, v233, v233, v115
	v_dot2_f32_bf16 v115, v234, v234, v115
	v_dot2_f32_bf16 v115, v235, v235, v115
	v_mfma_f32_16x16x32_bf16 v[116:119], v[14:17], v[232:235], v[116:119]
	s_nop 2
	v_mov_b32_e32 v120, v115
	s_nop 1
	v_permlane16_swap_b32_e32 v115, v120
	v_add_f32_e32 v115, v115, v120
	ds_bpermute_b32 v173, v248, v115
	v_cndmask_b32_e64 v116, v116, v117, s[66:67]
	v_cndmask_b32_e64 v116, v116, v118, s[40:41]
	v_cndmask_b32_e64 v116, v116, v119, s[68:69]
	s_waitcnt vmcnt(4)
	ds_write_b128 v244, v[58:61] offset:8192
	ds_write_b128 v245, v[50:53] offset:8192
	ds_write_b128 v246, v[54:57] offset:8192
	ds_write_b128 v247, v[62:65] offset:8192
	v_add_u32_e32 v0, v146, v147
	ds_read_b128 v[232:235], v0 offset:8192
	v_add_u32_e32 v0, v146, v148
	ds_read_b128 v[236:239], v0 offset:8192
	v_add_u32_e32 v0, v146, v149
	ds_read_b128 v[240:243], v0 offset:8192
	v_add_u32_e32 v0, v146, v150
	v_mov_b32_e32 v117, 0
	s_waitcnt lgkmcnt(2)
	v_dot2_f32_bf16 v117, v232, v232, v117
	v_dot2_f32_bf16 v117, v233, v233, v117
	v_dot2_f32_bf16 v117, v234, v234, v117
	v_dot2_f32_bf16 v117, v235, v235, v117
	v_mfma_f32_16x16x32_bf16 v[118:121], v[2:5], v[232:235], 0
	ds_read_b128 v[232:235], v0 offset:8192
	s_waitcnt lgkmcnt(2)
	v_dot2_f32_bf16 v117, v236, v236, v117
	v_dot2_f32_bf16 v117, v237, v237, v117
	v_dot2_f32_bf16 v117, v238, v238, v117
	v_dot2_f32_bf16 v117, v239, v239, v117
	v_mfma_f32_16x16x32_bf16 v[118:121], v[6:9], v[236:239], v[118:121]
	s_waitcnt lgkmcnt(1)
	v_dot2_f32_bf16 v117, v240, v240, v117
	v_dot2_f32_bf16 v117, v241, v241, v117
	v_dot2_f32_bf16 v117, v242, v242, v117
	v_dot2_f32_bf16 v117, v243, v243, v117
	v_mfma_f32_16x16x32_bf16 v[118:121], v[10:13], v[240:243], v[118:121]
	s_waitcnt lgkmcnt(0)
	v_dot2_f32_bf16 v117, v232, v232, v117
	v_dot2_f32_bf16 v117, v233, v233, v117
	v_dot2_f32_bf16 v117, v234, v234, v117
	v_dot2_f32_bf16 v117, v235, v235, v117
	v_mfma_f32_16x16x32_bf16 v[118:121], v[14:17], v[232:235], v[118:121]
	s_nop 2
	v_mov_b32_e32 v123, v117
	s_nop 1
	v_permlane16_swap_b32_e32 v117, v123
	v_add_f32_e32 v117, v117, v123
	ds_bpermute_b32 v174, v248, v117
	v_cndmask_b32_e64 v118, v118, v119, s[66:67]
	v_cndmask_b32_e64 v118, v118, v120, s[40:41]
	v_cndmask_b32_e64 v118, v118, v121, s[68:69]
	s_waitcnt vmcnt(0)
	ds_write_b128 v244, v[74:77] offset:12288
	ds_write_b128 v245, v[66:69] offset:12288
	ds_write_b128 v246, v[70:73] offset:12288
	ds_write_b128 v247, v[78:81] offset:12288
	v_add_u32_e32 v0, v146, v147
	ds_read_b128 v[232:235], v0 offset:12288
	v_add_u32_e32 v0, v146, v148
	ds_read_b128 v[236:239], v0 offset:12288
	v_add_u32_e32 v0, v146, v149
	ds_read_b128 v[240:243], v0 offset:12288
	v_add_u32_e32 v0, v146, v150
	v_mov_b32_e32 v119, 0
	s_waitcnt lgkmcnt(2)
; #define LAS __attribute__((address_space(3)))
;     ...
;           for (int jj = 0; jj < 4; ++jj) {
;               const int rho = jj * 16 + c16, slot = b * 64 + rho;
;               f32x4 a = {0.f, 0.f, 0.f, 0.f}; float ss = 0.f;
; #pragma unroll
;               for (int ks = 0; ks < 4; ++ks) {
; #pragma unroll
;                   for (int e = 0; e < 4; ++e) asm("v_dot2_f32_bf16 %0, %1, %1, %0" : "+v"(ss) : "v"(w[jj][ks][e]));
;                   a = __builtin_amdgcn_mfma_f32_16x16x32_bf16(qa[ks], *reinterpret_cast<const bf16x8*>(&w[jj][ks]), a, 0, 0, 0);
;                   *(LAS u32x4*)(wbase + rho * 256 + (((ks * 4 + quad) ^ fsw) << 4)) = w[jj][ks]; }
;               ss += __shfl_xor(ss, 16); ss += __shfl_xor(ss, 32);
;               const float rstd = rsqrtf(ss * (1.f / 128.f) + EPS);
;               const float av = quad == 0 ? a[0] : (quad == 1 ? a[1] : (quad == 2 ? a[2] : a[3]));
;               rsv[jj] = rstd; lgv[jj] = (slot < kcount) ? av * rstd * 0.08838834764831845f : -__builtin_inff();
;           }
;     ...
;         if (it < N_D) { if (!(tmask & 1)) continue; const int qb = 15 - (it >> 4), bh = it & 15; item_fox(p, l, bh >> 2, bh & 3, qb, lds); }
;         else if (it < N_D + N_B) { if (!(tmask & 2)) continue; const int j = it - N_D; const int rq = 511 - (j >> 2), bl = j & 3; item_dsa(p, bl, rq, lds, smask); }
	v_dot2_f32_bf16 v119, v232, v232, v119
	v_dot2_f32_bf16 v119, v233, v233, v119
	v_dot2_f32_bf16 v119, v234, v234, v119
	v_dot2_f32_bf16 v119, v235, v235, v119
	v_mfma_f32_16x16x32_bf16 v[176:179], v[2:5], v[232:235], 0
	ds_read_b128 v[232:235], v0 offset:12288
	s_waitcnt lgkmcnt(2)
	v_dot2_f32_bf16 v119, v236, v236, v119
	v_dot2_f32_bf16 v119, v237, v237, v119
	v_dot2_f32_bf16 v119, v238, v238, v119
	v_dot2_f32_bf16 v119, v239, v239, v119
	v_mfma_f32_16x16x32_bf16 v[176:179], v[6:9], v[236:239], v[176:179]
	s_waitcnt lgkmcnt(1)
	v_dot2_f32_bf16 v119, v240, v240, v119
	v_dot2_f32_bf16 v119, v241, v241, v119
	v_dot2_f32_bf16 v119, v242, v242, v119
	v_dot2_f32_bf16 v119, v243, v243, v119
	v_mfma_f32_16x16x32_bf16 v[176:179], v[10:13], v[240:243], v[176:179]
	s_waitcnt lgkmcnt(0)
	v_dot2_f32_bf16 v119, v232, v232, v119
	v_dot2_f32_bf16 v119, v233, v233, v119
	v_dot2_f32_bf16 v119, v234, v234, v119
	v_dot2_f32_bf16 v119, v235, v235, v119
	v_mfma_f32_16x16x32_bf16 v[120:123], v[14:17], v[232:235], v[176:179]
	s_nop 2
	v_mov_b32_e32 v0, v119
	s_nop 1
	v_permlane16_swap_b32_e32 v119, v0
	v_add_f32_e32 v119, v119, v0
	ds_bpermute_b32 v175, v248, v119
	v_cndmask_b32_e64 v120, v120, v121, s[66:67]
	v_cndmask_b32_e64 v120, v120, v122, s[40:41]
	v_cndmask_b32_e64 v120, v120, v123, s[68:69]
	s_add_i32 s24, s24, 1
	s_cmp_lg_u32 s59, 0
	s_cbranch_scc1 .Lqpf_skip
	v_readfirstlane_b32 s0, v180
	s_nop 3
	s_sub_i32 s0, s0, 0x100
	s_cmp_lt_u32 s0, 0x800
	s_cbranch_scc0 .Lqpf_skip
	s_lshr_b32 s1, s0, 2
	s_sub_i32 s1, 0x1ff, s1
	s_lshl_b32 s1, s1, 3
	s_and_b32 s0, s0, 3
	s_lshl_b32 s0, s0, 12
	s_add_i32 s0, s0, s1
	v_lshrrev_b32_e32 v225, 3, v163
	v_add_u32_e32 v225, s0, v225
	v_mul_u32_u24_e32 v225, 0x5800, v225
	v_and_b32_e32 v226, 7, v163
	v_lshl_add_u32 v225, v226, 7, v225
	v_add_u32_e32 v225, 0x1000, v225
	global_load_dword v224, v225, s[14:15]
; #define LAS __attribute__((address_space(3)))
; __device__ __forceinline__ u16 f2bf(float f) { return (u16)(cvtpk(f, 0.f) & 0xffffu); }
;     ...
;           if (b + 1 < nb) gl(b + 1);
;           float mx = fmaxf(fmaxf(lgv[0], lgv[1]), fmaxf(lgv[2], lgv[3]));
; #pragma unroll
;           for (int o = 1; o < 16; o <<= 1) mx = fmaxf(mx, __shfl_xor(mx, o));
;           const float mnew = fmaxf(mrun, mx), alpha = __expf(mrun - mnew); mrun = mnew;
;           float ps = 0.f;
; #pragma unroll
;           for (int jj = 0; jj < 4; ++jj) { const float pe = __expf(lgv[jj] - mnew); ps += pe; pbT[quad * 64 + jj * 16 + c16] = f2bf(pe * rsv[jj]); }
;           lsum = lsum * alpha + ps;
;           if (c16 == 0) alf[quad] = alpha;
;           const f32x4 al4 = *(const LAS f32x4*)alf;
; #pragma unroll
;           for (int c = 0; c < 8; ++c) oacc[c] *= al4;
; #pragma unroll
;           for (int ks = 0; ks < 2; ++ks) {
;               const bf16x8 pf = *(const LAS bf16x8*)(pbT + (c16 & 3) * 64 + ks * 32 + quad * 8);
;               u16x4 t0[8], t1[8];
;     ...
;               if (ks == 0) { TRR8(t0, 0, 0); TRR8(t1, 1, 0); } else { TRR8(t0, 0, 8192); TRR8(t1, 1, 8192); }
;     ...
; #pragma unroll
;               for (int c = 0; c < 8; ++c) {
;                   const bf16x8 bf = {(short)t0[c][0], (short)t0[c][1], (short)t0[c][2], (short)t0[c][3], (short)t1[c][0], (short)t1[c][1], (short)t1[c][2], (short)t1[c][3]};
;                   oacc[c] = __builtin_amdgcn_mfma_f32_16x16x32_bf16(pf, bf, oacc[c], 0, 0, 0);
;               }
;           }
.Lqpf_skip:
.LBB0_946:
	s_waitcnt lgkmcnt(0)
	v_add_f32_e32 v119, v119, v175
	v_add_f32_e32 v117, v117, v174
	v_add_f32_e32 v115, v115, v173
	v_add_f32_e32 v0, v161, v172
	v_fmamk_f32 v119, v119, 0x3c000000, v199
	v_fmamk_f32 v117, v117, 0x3c000000, v199
	v_fmamk_f32 v115, v115, 0x3c000000, v199
	v_fmamk_f32 v0, v0, 0x3c000000, v199
	v_rsq_f32_e32 v122, v119
	v_rsq_f32_e32 v123, v117
	v_rsq_f32_e32 v125, v115
	v_rsq_f32_e32 v161, v0
	v_add_u32_e32 v0, 48, v157
	v_add_u32_e32 v115, 32, v157
	v_mul_f32_e32 v119, v122, v120
	v_cmp_gt_i32_e32 vcc, s22, v0
	v_mul_f32_e32 v117, v123, v118
	v_mul_f32_e32 v119, 0x3db504f3, v119
	v_cndmask_b32_e32 v121, v208, v119, vcc
	v_cmp_gt_i32_e32 vcc, s22, v115
	v_mul_f32_e32 v117, 0x3db504f3, v117
	v_add_u32_e32 v0, 16, v157
	v_cndmask_b32_e32 v120, v208, v117, vcc
	v_mul_f32_e32 v119, v125, v116
	v_cmp_gt_i32_e32 vcc, s22, v0
	v_mul_f32_e32 v119, 0x3db504f3, v119
	v_mul_f32_e32 v0, v161, v114
	v_cndmask_b32_e32 v119, v208, v119, vcc
	v_cmp_gt_i32_e32 vcc, s22, v157
	v_mul_f32_e32 v0, 0x3db504f3, v0
	s_nop 0
	v_cndmask_b32_e32 v118, v208, v0, vcc
	v_max_f32_e32 v0, v120, v121
	v_max3_f32 v114, v118, v119, v0
	s_nop 1
	v_max_f32_dpp v115, v114, v114 quad_perm:[1,0,3,2] row_mask:0xf bank_mask:0xf
	s_nop 1
	v_max_f32_dpp v116, v115, v115 quad_perm:[2,3,0,1] row_mask:0xf bank_mask:0xf
	s_nop 1
	v_max_f32_dpp v117, v116, v116 row_ror:4 row_mask:0xf bank_mask:0xf
	s_nop 1
	v_max_f32_dpp v172, v117, v117 row_ror:8 row_mask:0xf bank_mask:0xf
	v_max3_f32 v117, v160, v117, v172
	v_sub_f32_e32 v118, v118, v117
	v_sub_f32_e32 v119, v119, v117
	v_sub_f32_e32 v120, v120, v117
	v_sub_f32_e32 v121, v121, v117
	v_mul_f32_e32 v118, 0x3fb8aa3b, v118
	v_mul_f32_e32 v119, 0x3fb8aa3b, v119
	v_mul_f32_e32 v120, 0x3fb8aa3b, v120
	v_mul_f32_e32 v121, 0x3fb8aa3b, v121
	v_exp_f32_e32 v118, v118
	v_exp_f32_e32 v119, v119
	v_exp_f32_e32 v120, v120
	v_exp_f32_e32 v121, v121
	v_sub_f32_e32 v160, v160, v117
	v_mul_f32_e32 v161, v161, v118
	v_mul_f32_e32 v125, v125, v119
	v_mul_f32_e32 v123, v123, v120
	v_mul_f32_e32 v122, v122, v121
	v_mul_f32_e32 v160, 0x3fb8aa3b, v160
	v_cvt_pk_bf16_f32 v161, v161, v1
	ds_write_b16 v155, v161 offset:1024
	v_cvt_pk_bf16_f32 v125, v125, v1
	ds_write_b16 v155, v125 offset:1056
	v_cvt_pk_bf16_f32 v123, v123, v1
	ds_write_b16 v155, v123 offset:1088
	v_cvt_pk_bf16_f32 v122, v122, v1
	ds_write_b16 v155, v122 offset:1120
	v_exp_f32_e32 v122, v160
	s_and_saveexec_b64 s[0:1], s[38:39]
	ds_write_b32 v129, v122 offset:640
	s_or_b64 exec, exec, s[0:1]
	v_add_f32_e32 v118, 0, v118
	v_add_f32_e32 v118, v119, v118
	v_add_f32_e32 v118, v120, v118
	v_add_f32_e32 v118, v121, v118
	v_mov_b32_e32 v119, s56
	v_fmac_f32_e32 v118, v159, v122
	ds_read_b128 v[120:123], v119 offset:640
	v_add_u32_e32 v154, 0x80, v154
	v_add_u32_e32 v157, 64, v157
	s_cmp_eq_u32 s23, s24
	s_waitcnt lgkmcnt(0)
	v_mul_f32_e32 v174, v92, v122
	v_mul_f32_e32 v175, v93, v123
	v_mul_f32_e32 v172, v90, v120
	v_mul_f32_e32 v173, v91, v121
	v_mul_f32_e32 v92, v96, v122
	v_mul_f32_e32 v93, v97, v123
	v_mul_f32_e32 v90, v94, v120
	v_mul_f32_e32 v91, v95, v121
	ds_read_b128 v[94:97], v156 offset:1024
	ds_read_b64_tr_b16 v[216:217], v130 offset:0
	ds_read_b64_tr_b16 v[218:219], v138 offset:0
	ds_read_b64_tr_b16 v[212:213], v131 offset:0
	ds_read_b64_tr_b16 v[214:215], v139 offset:0
	ds_read_b64_tr_b16 v[194:195], v132 offset:0
	ds_read_b64_tr_b16 v[196:197], v140 offset:0
	ds_read_b64_tr_b16 v[190:191], v133 offset:0
	ds_read_b64_tr_b16 v[192:193], v141 offset:0
	ds_read_b64_tr_b16 v[186:187], v134 offset:0
	ds_read_b64_tr_b16 v[188:189], v142 offset:0
	v_mul_f32_e32 v106, v106, v120
	v_mul_f32_e32 v107, v107, v121
	v_mul_f32_e32 v110, v110, v120
	v_mul_f32_e32 v111, v111, v121
	v_mul_f32_e32 v176, v82, v120
	v_mul_f32_e32 v177, v83, v121
	v_mul_f32_e32 v182, v86, v120
	v_mul_f32_e32 v183, v87, v121
	v_mul_f32_e32 v86, v102, v120
	v_mul_f32_e32 v87, v103, v121
	v_mul_f32_e32 v82, v98, v120
	v_mul_f32_e32 v83, v99, v121
	v_mul_f32_e32 v108, v108, v122
	v_mul_f32_e32 v109, v109, v123
	v_mul_f32_e32 v112, v112, v122
	v_mul_f32_e32 v113, v113, v123
	v_mul_f32_e32 v178, v84, v122
	v_mul_f32_e32 v179, v85, v123
	v_mul_f32_e32 v184, v88, v122
	v_mul_f32_e32 v185, v89, v123
	v_mul_f32_e32 v88, v104, v122
	v_mul_f32_e32 v89, v105, v123
	v_mul_f32_e32 v84, v100, v122
	v_mul_f32_e32 v85, v101, v123
	ds_read_b64_tr_b16 v[120:121], v135 offset:0
	ds_read_b64_tr_b16 v[122:123], v143 offset:0
	ds_read_b64_tr_b16 v[102:103], v136 offset:0
	ds_read_b64_tr_b16 v[104:105], v144 offset:0
	s_waitcnt lgkmcnt(12)
	v_mfma_f32_16x16x32_bf16 v[106:109], v[94:97], v[216:219], v[106:109]
	ds_read_b64_tr_b16 v[98:99], v137 offset:0
	ds_read_b64_tr_b16 v[100:101], v145 offset:0
	s_waitcnt lgkmcnt(12)
	v_mfma_f32_16x16x32_bf16 v[110:113], v[94:97], v[212:215], v[110:113]
	s_waitcnt lgkmcnt(10)
	v_mfma_f32_16x16x32_bf16 v[172:175], v[94:97], v[194:197], v[172:175]
	s_waitcnt lgkmcnt(8)
	v_mfma_f32_16x16x32_bf16 v[176:179], v[94:97], v[190:193], v[176:179]
	s_waitcnt lgkmcnt(6)
	v_mfma_f32_16x16x32_bf16 v[182:185], v[94:97], v[186:189], v[182:185]
	s_waitcnt lgkmcnt(4)
	v_mfma_f32_16x16x32_bf16 v[120:123], v[94:97], v[120:123], v[90:93]
	s_waitcnt lgkmcnt(2)
	v_mfma_f32_16x16x32_bf16 v[102:105], v[94:97], v[102:105], v[86:89]
	s_waitcnt lgkmcnt(0)
	v_mfma_f32_16x16x32_bf16 v[98:101], v[94:97], v[98:101], v[82:85]
	ds_read_b128 v[220:223], v156 offset:1088
	ds_read_b64_tr_b16 v[212:213], v130 offset:8192
	ds_read_b64_tr_b16 v[214:215], v138 offset:8192
	ds_read_b64_tr_b16 v[194:195], v131 offset:8192
	ds_read_b64_tr_b16 v[196:197], v139 offset:8192
	ds_read_b64_tr_b16 v[90:91], v132 offset:8192
	ds_read_b64_tr_b16 v[92:93], v140 offset:8192
	ds_read_b64_tr_b16 v[82:83], v133 offset:8192
	ds_read_b64_tr_b16 v[84:85], v141 offset:8192
	ds_read_b64_tr_b16 v[86:87], v134 offset:8192
	ds_read_b64_tr_b16 v[88:89], v142 offset:8192
	ds_read_b64_tr_b16 v[94:95], v135 offset:8192
	ds_read_b64_tr_b16 v[96:97], v143 offset:8192
	ds_read_b64_tr_b16 v[190:191], v136 offset:8192
	ds_read_b64_tr_b16 v[192:193], v144 offset:8192
	s_waitcnt lgkmcnt(12)
	v_mfma_f32_16x16x32_bf16 v[106:109], v[220:223], v[212:215], v[106:109]
	ds_read_b64_tr_b16 v[186:187], v137 offset:8192
	ds_read_b64_tr_b16 v[188:189], v145 offset:8192
	s_waitcnt lgkmcnt(12)
	v_mfma_f32_16x16x32_bf16 v[110:113], v[220:223], v[194:197], v[110:113]
	s_waitcnt lgkmcnt(10)
	v_mfma_f32_16x16x32_bf16 v[90:93], v[220:223], v[90:93], v[172:175]
	s_waitcnt lgkmcnt(8)
	v_mfma_f32_16x16x32_bf16 v[82:85], v[220:223], v[82:85], v[176:179]
	s_waitcnt lgkmcnt(6)
	v_mfma_f32_16x16x32_bf16 v[86:89], v[220:223], v[86:89], v[182:185]
	s_waitcnt lgkmcnt(4)
	v_mfma_f32_16x16x32_bf16 v[94:97], v[220:223], v[94:97], v[120:123]
	s_waitcnt lgkmcnt(2)
	v_mfma_f32_16x16x32_bf16 v[102:105], v[220:223], v[190:193], v[102:105]
	s_waitcnt lgkmcnt(0)
	v_mfma_f32_16x16x32_bf16 v[98:101], v[220:223], v[186:189], v[98:101]
	s_cbranch_scc1 .LBB0_952
	v_mov_b32_e32 v159, v118
	v_mov_b32_e32 v160, v117
	s_branch .LBB0_928
